# epilogue de-serialisation (second-half residual loads issued with the first half in P3/P8, P5, P10) on top of the role-independent merge
# baseline (speedup 1.0000x reference)
.LBB0_726:
	v_lshl_or_b32 v130, s50, 8, v191
	v_lshl_add_u32 v168, s51, 8, v176
	v_ashrrev_i32_e32 v131, 31, v130
	v_lshlrev_b64 v[170:171], 1, v[130:131]
	v_or_b32_e32 v130, 16, v168
	v_ashrrev_i32_e32 v131, 31, v130
	v_lshlrev_b64 v[130:131], 11, v[130:131]
	v_lshl_add_u64 v[130:131], s[64:65], 0, v[130:131]
	v_lshl_add_u64 v[186:187], v[130:131], 0, v[170:171]
	v_or_b32_e32 v130, 32, v168
	v_ashrrev_i32_e32 v131, 31, v130
	v_lshlrev_b64 v[130:131], 11, v[130:131]
	v_lshl_add_u64 v[130:131], s[64:65], 0, v[130:131]
	v_lshl_add_u64 v[174:175], v[130:131], 0, v[170:171]
	v_or_b32_e32 v130, 48, v168
	v_ashrrev_i32_e32 v169, 31, v168
	v_ashrrev_i32_e32 v131, 31, v130
	v_lshlrev_b64 v[132:133], 11, v[168:169]
	v_lshlrev_b64 v[130:131], 11, v[130:131]
	v_lshl_add_u64 v[132:133], s[64:65], 0, v[132:133]
	v_lshl_add_u64 v[130:131], s[64:65], 0, v[130:131]
	v_lshl_add_u64 v[188:189], v[132:133], 0, v[170:171]
	v_lshl_add_u64 v[172:173], v[130:131], 0, v[170:171]
	s_mov_b32 s98, 0x40000
	s_mov_b32 s99, 0
	v_lshl_add_u64 v[166:167], v[188:189], 0, s[98:99]
	global_load_dwordx4 v[226:229], v[166:167], off
	global_load_dwordx4 v[194:197], v[188:189], off
	v_lshl_add_u64 v[166:167], v[188:189], 0, s[98:99]
	global_load_dwordx4 v[230:233], v[166:167], off offset:256
	global_load_dwordx4 v[154:157], v[188:189], off offset:256
	v_lshl_add_u64 v[166:167], v[186:187], 0, s[98:99]
	global_load_dwordx4 v[234:237], v[166:167], off
	global_load_dwordx4 v[150:153], v[186:187], off
	v_lshl_add_u64 v[166:167], v[186:187], 0, s[98:99]
	global_load_dwordx4 v[240:243], v[166:167], off offset:256
	global_load_dwordx4 v[146:149], v[186:187], off offset:256
	v_lshl_add_u64 v[166:167], v[174:175], 0, s[98:99]
	global_load_dwordx4 v[244:247], v[166:167], off
	global_load_dwordx4 v[142:145], v[174:175], off
	v_lshl_add_u64 v[166:167], v[174:175], 0, s[98:99]
	global_load_dwordx4 v[248:251], v[166:167], off offset:256
	global_load_dwordx4 v[138:141], v[174:175], off offset:256
	v_lshl_add_u64 v[166:167], v[172:173], 0, s[98:99]
	global_load_dwordx4 v[158:161], v[166:167], off
	global_load_dwordx4 v[134:137], v[172:173], off
	v_lshl_add_u64 v[166:167], v[172:173], 0, s[98:99]
	global_load_dwordx4 v[162:165], v[166:167], off offset:256
	global_load_dwordx4 v[130:133], v[172:173], off offset:256
	s_waitcnt vmcnt(0)
	v_lshlrev_b32_e32 v198, 16, v194
	v_and_b32_e32 v199, 0xffff0000, v194
	v_lshlrev_b32_e32 v194, 16, v195
	v_and_b32_e32 v195, 0xffff0000, v195
	v_pk_add_f32 v[128:129], v[128:129], v[194:195]
	v_lshlrev_b32_e32 v194, 16, v196
	v_and_b32_e32 v195, 0xffff0000, v196
	v_lshlrev_b32_e32 v196, 16, v197
	v_and_b32_e32 v197, 0xffff0000, v197
	v_cndmask_b32_e64 v193, 0, 1, s[94:95]
	v_pk_add_f32 v[126:127], v[126:127], v[198:199]
	v_pk_add_f32 v[124:125], v[124:125], v[196:197]
	v_cmp_ne_u32_e64 s[42:43], 1, v193
	s_andn2_b64 vcc, exec, s[94:95]
	v_pk_add_f32 v[122:123], v[122:123], v[194:195]
	s_cbranch_vccnz .LBB0_728
	v_cvt_pk_bf16_f32 v194, v126, v127
	v_cvt_pk_bf16_f32 v195, v128, v129
	v_cvt_pk_bf16_f32 v196, v122, v123
	v_cvt_pk_bf16_f32 v197, v124, v125
	global_store_dwordx4 v[188:189], v[194:197], off

.LBB0_742:
	v_mul_f32_e32 v79, v79, v79
	v_mul_f32_e32 v75, v75, v75
	v_mul_f32_e32 v71, v71, v71
	v_mul_f32_e32 v67, v67, v67
	v_fmac_f32_e32 v79, v78, v78
	v_mul_f32_e32 v78, v81, v81
	v_fmac_f32_e32 v75, v74, v74
	v_mul_f32_e32 v74, v77, v77
	v_fmac_f32_e32 v71, v70, v70
	v_mul_f32_e32 v70, v73, v73
	v_fmac_f32_e32 v67, v66, v66
	v_mul_f32_e32 v66, v69, v69
	v_fmac_f32_e32 v78, v80, v80
	v_fmac_f32_e32 v74, v76, v76
	v_fmac_f32_e32 v70, v72, v72
	v_fmac_f32_e32 v66, v68, v68
	v_add_f32_e32 v78, v79, v78
	v_add_f32_e32 v74, v75, v74
	v_add_f32_e32 v70, v71, v70
	v_add_f32_e32 v66, v67, v66
	v_add_f32_e32 v74, v78, v74
	v_add_f32_e32 v66, v70, v66
	v_add_f32_e32 v66, v74, v66
	ds_bpermute_b32 v67, v122, v66
	s_waitcnt lgkmcnt(0)
	v_add_f32_e32 v106, v66, v67
	v_add_u32_e32 v66, 0x80, v168
	v_ashrrev_i32_e32 v67, 31, v66
	v_lshlrev_b64 v[66:67], 11, v[66:67]
	v_lshl_add_u64 v[66:67], s[64:65], 0, v[66:67]
	v_lshl_add_u64 v[100:101], v[66:67], 0, v[170:171]
	v_add_u32_e32 v66, 0x90, v168
	v_ashrrev_i32_e32 v67, 31, v66
	v_lshlrev_b64 v[66:67], 11, v[66:67]
	v_lshl_add_u64 v[66:67], s[64:65], 0, v[66:67]
	v_lshl_add_u64 v[98:99], v[66:67], 0, v[170:171]
	v_add_u32_e32 v66, 0xa0, v168
	v_ashrrev_i32_e32 v67, 31, v66
	v_lshlrev_b64 v[66:67], 11, v[66:67]
	v_lshl_add_u64 v[66:67], s[64:65], 0, v[66:67]
	v_lshl_add_u64 v[96:97], v[66:67], 0, v[170:171]
	v_add_u32_e32 v66, 0xb0, v168
	v_ashrrev_i32_e32 v67, 31, v66
	v_lshlrev_b64 v[66:67], 11, v[66:67]
	v_lshl_add_u64 v[66:67], s[64:65], 0, v[66:67]
	v_lshl_add_u64 v[94:95], v[66:67], 0, v[170:171]
	ds_bpermute_b32 v107, v116, v106
	v_lshlrev_b32_e32 v112, 16, v226
	v_and_b32_e32 v113, 0xffff0000, v226
	v_lshlrev_b32_e32 v108, 16, v227
	v_and_b32_e32 v109, 0xffff0000, v227
	v_pk_add_f32 v[64:65], v[64:65], v[108:109]
	v_lshlrev_b32_e32 v108, 16, v228
	v_and_b32_e32 v109, 0xffff0000, v228
	v_lshlrev_b32_e32 v110, 16, v229
	v_and_b32_e32 v111, 0xffff0000, v229
	v_pk_add_f32 v[62:63], v[62:63], v[112:113]
	v_pk_add_f32 v[60:61], v[60:61], v[110:111]
	s_and_b64 vcc, exec, s[42:43]
	v_pk_add_f32 v[58:59], v[58:59], v[108:109]
	s_cbranch_vccnz .LBB0_744
	v_cvt_pk_bf16_f32 v108, v62, v63
	v_cvt_pk_bf16_f32 v109, v64, v65
	v_cvt_pk_bf16_f32 v110, v58, v59
	v_cvt_pk_bf16_f32 v111, v60, v61
	global_store_dwordx4 v[100:101], v[108:111], off
.LBB0_744:
	s_nop 0
	v_lshlrev_b32_e32 v108, 16, v230
	v_and_b32_e32 v109, 0xffff0000, v230
	v_lshlrev_b32_e32 v90, 16, v231
	v_and_b32_e32 v91, 0xffff0000, v231
	v_pk_add_f32 v[56:57], v[56:57], v[90:91]
	v_lshlrev_b32_e32 v90, 16, v232
	v_and_b32_e32 v91, 0xffff0000, v232
	v_lshlrev_b32_e32 v92, 16, v233
	v_and_b32_e32 v93, 0xffff0000, v233
	v_pk_add_f32 v[54:55], v[54:55], v[108:109]
	v_pk_add_f32 v[52:53], v[52:53], v[92:93]
	s_and_b64 vcc, exec, s[42:43]
	v_pk_add_f32 v[50:51], v[50:51], v[90:91]
	s_cbranch_vccnz .LBB0_746
	v_cvt_pk_bf16_f32 v90, v54, v55
	v_cvt_pk_bf16_f32 v91, v56, v57
	v_cvt_pk_bf16_f32 v92, v50, v51
	v_cvt_pk_bf16_f32 v93, v52, v53
	global_store_dwordx4 v[100:101], v[90:93], off offset:256
.LBB0_746:
	v_mul_f32_e32 v63, v63, v63
	v_mul_f32_e32 v59, v59, v59
	v_mul_f32_e32 v55, v55, v55
	v_mul_f32_e32 v51, v51, v51
	v_fmac_f32_e32 v63, v62, v62
	v_mul_f32_e32 v62, v65, v65
	v_fmac_f32_e32 v59, v58, v58
	v_mul_f32_e32 v58, v61, v61
	v_fmac_f32_e32 v55, v54, v54
	v_mul_f32_e32 v54, v57, v57
	v_fmac_f32_e32 v51, v50, v50
	v_mul_f32_e32 v50, v53, v53
	v_fmac_f32_e32 v62, v64, v64
	v_fmac_f32_e32 v58, v60, v60
	v_fmac_f32_e32 v54, v56, v56
	v_fmac_f32_e32 v50, v52, v52
	v_add_f32_e32 v62, v63, v62
	v_add_f32_e32 v58, v59, v58
	v_add_f32_e32 v54, v55, v54
	v_add_f32_e32 v50, v51, v50
	v_add_f32_e32 v58, v62, v58
	v_add_f32_e32 v50, v54, v50
	v_add_f32_e32 v50, v58, v50
	ds_bpermute_b32 v51, v122, v50
	v_lshlrev_b32_e32 v52, 16, v234
	v_and_b32_e32 v53, 0xffff0000, v234
	v_lshlrev_b32_e32 v54, 16, v235
	v_and_b32_e32 v55, 0xffff0000, v235
	s_waitcnt lgkmcnt(0)
	v_add_f32_e32 v50, v50, v51
	ds_bpermute_b32 v51, v116, v50
	v_pk_add_f32 v[48:49], v[48:49], v[54:55]
	v_pk_add_f32 v[46:47], v[46:47], v[52:53]
	v_lshlrev_b32_e32 v52, 16, v236
	v_and_b32_e32 v53, 0xffff0000, v236
	v_lshlrev_b32_e32 v54, 16, v237
	v_and_b32_e32 v55, 0xffff0000, v237
	v_pk_add_f32 v[44:45], v[44:45], v[54:55]
	s_and_b64 vcc, exec, s[42:43]
	v_pk_add_f32 v[42:43], v[42:43], v[52:53]
	s_cbranch_vccnz .LBB0_748
	v_cvt_pk_bf16_f32 v52, v46, v47
	v_cvt_pk_bf16_f32 v53, v48, v49
	v_cvt_pk_bf16_f32 v54, v42, v43
	v_cvt_pk_bf16_f32 v55, v44, v45
	global_store_dwordx4 v[98:99], v[52:55], off
.LBB0_748:
	s_nop 0
	v_lshlrev_b32_e32 v52, 16, v240
	v_and_b32_e32 v53, 0xffff0000, v240
	v_lshlrev_b32_e32 v54, 16, v241
	v_and_b32_e32 v55, 0xffff0000, v241
	v_pk_add_f32 v[40:41], v[40:41], v[54:55]
	v_pk_add_f32 v[38:39], v[38:39], v[52:53]
	v_lshlrev_b32_e32 v52, 16, v242
	v_and_b32_e32 v53, 0xffff0000, v242
	v_lshlrev_b32_e32 v54, 16, v243
	v_and_b32_e32 v55, 0xffff0000, v243
	v_pk_add_f32 v[36:37], v[36:37], v[54:55]
	s_and_b64 vcc, exec, s[42:43]
	v_pk_add_f32 v[34:35], v[34:35], v[52:53]
	s_cbranch_vccnz .LBB0_750
	v_cvt_pk_bf16_f32 v52, v38, v39
	v_cvt_pk_bf16_f32 v53, v40, v41
	v_cvt_pk_bf16_f32 v54, v34, v35
	v_cvt_pk_bf16_f32 v55, v36, v37
	global_store_dwordx4 v[98:99], v[52:55], off offset:256
.LBB0_750:
	v_mul_f32_e32 v47, v47, v47
	v_mul_f32_e32 v43, v43, v43
	v_mul_f32_e32 v39, v39, v39
	v_mul_f32_e32 v35, v35, v35
	v_fmac_f32_e32 v47, v46, v46
	v_mul_f32_e32 v46, v49, v49
	v_fmac_f32_e32 v43, v42, v42
	v_mul_f32_e32 v42, v45, v45
	v_fmac_f32_e32 v39, v38, v38
	v_mul_f32_e32 v38, v41, v41
	v_fmac_f32_e32 v35, v34, v34
	v_mul_f32_e32 v34, v37, v37
	v_fmac_f32_e32 v46, v48, v48
	v_fmac_f32_e32 v42, v44, v44
	v_fmac_f32_e32 v38, v40, v40
	v_fmac_f32_e32 v34, v36, v36
	v_add_f32_e32 v46, v47, v46
	v_add_f32_e32 v42, v43, v42
	v_add_f32_e32 v38, v39, v38
	v_add_f32_e32 v34, v35, v34
	v_add_f32_e32 v42, v46, v42
	v_add_f32_e32 v34, v38, v34
	v_add_f32_e32 v34, v42, v34
	ds_bpermute_b32 v35, v122, v34
	v_lshlrev_b32_e32 v36, 16, v244
	v_and_b32_e32 v37, 0xffff0000, v244
	v_lshlrev_b32_e32 v38, 16, v245
	v_and_b32_e32 v39, 0xffff0000, v245
	s_waitcnt lgkmcnt(0)
	v_add_f32_e32 v34, v34, v35
	ds_bpermute_b32 v35, v116, v34
	v_pk_add_f32 v[32:33], v[32:33], v[38:39]
	v_pk_add_f32 v[30:31], v[30:31], v[36:37]
	v_lshlrev_b32_e32 v36, 16, v246
	v_and_b32_e32 v37, 0xffff0000, v246
	v_lshlrev_b32_e32 v38, 16, v247
	v_and_b32_e32 v39, 0xffff0000, v247
	v_pk_add_f32 v[28:29], v[28:29], v[38:39]
	s_and_b64 vcc, exec, s[42:43]
	v_pk_add_f32 v[26:27], v[26:27], v[36:37]
	s_cbranch_vccnz .LBB0_752
	v_cvt_pk_bf16_f32 v36, v30, v31
	v_cvt_pk_bf16_f32 v37, v32, v33
	v_cvt_pk_bf16_f32 v38, v26, v27
	v_cvt_pk_bf16_f32 v39, v28, v29
	global_store_dwordx4 v[96:97], v[36:39], off
.LBB0_752:
	s_nop 0
	v_lshlrev_b32_e32 v36, 16, v248
	v_and_b32_e32 v37, 0xffff0000, v248
	v_lshlrev_b32_e32 v38, 16, v249
	v_and_b32_e32 v39, 0xffff0000, v249
	v_pk_add_f32 v[24:25], v[24:25], v[38:39]
	v_pk_add_f32 v[22:23], v[22:23], v[36:37]
	v_lshlrev_b32_e32 v36, 16, v250
	v_and_b32_e32 v37, 0xffff0000, v250
	v_lshlrev_b32_e32 v38, 16, v251
	v_and_b32_e32 v39, 0xffff0000, v251
	v_pk_add_f32 v[20:21], v[20:21], v[38:39]
	s_and_b64 vcc, exec, s[42:43]
	v_pk_add_f32 v[18:19], v[18:19], v[36:37]
	s_cbranch_vccnz .LBB0_754
	v_cvt_pk_bf16_f32 v36, v22, v23
	v_cvt_pk_bf16_f32 v37, v24, v25
	v_cvt_pk_bf16_f32 v38, v18, v19
	v_cvt_pk_bf16_f32 v39, v20, v21
	global_store_dwordx4 v[96:97], v[36:39], off offset:256
.LBB0_754:
	v_mul_f32_e32 v31, v31, v31
	v_mul_f32_e32 v27, v27, v27
	v_mul_f32_e32 v23, v23, v23
	v_mul_f32_e32 v19, v19, v19
	v_fmac_f32_e32 v31, v30, v30
	v_mul_f32_e32 v30, v33, v33
	v_fmac_f32_e32 v27, v26, v26
	v_mul_f32_e32 v26, v29, v29
	v_fmac_f32_e32 v23, v22, v22
	v_mul_f32_e32 v22, v25, v25
	v_fmac_f32_e32 v19, v18, v18
	v_mul_f32_e32 v18, v21, v21
	v_fmac_f32_e32 v30, v32, v32
	v_fmac_f32_e32 v26, v28, v28
	v_fmac_f32_e32 v22, v24, v24
	v_fmac_f32_e32 v18, v20, v20
	v_add_f32_e32 v30, v31, v30
	v_add_f32_e32 v26, v27, v26
	v_add_f32_e32 v22, v23, v22
	v_add_f32_e32 v18, v19, v18
	v_add_f32_e32 v26, v30, v26
	v_add_f32_e32 v18, v22, v18
	v_add_f32_e32 v18, v26, v18
	ds_bpermute_b32 v19, v122, v18
	v_lshlrev_b32_e32 v20, 16, v158
	v_and_b32_e32 v21, 0xffff0000, v158
	v_lshlrev_b32_e32 v22, 16, v159
	v_and_b32_e32 v23, 0xffff0000, v159
	s_waitcnt lgkmcnt(0)
	v_add_f32_e32 v18, v18, v19
	ds_bpermute_b32 v19, v116, v18
	v_pk_add_f32 v[16:17], v[16:17], v[22:23]
	v_pk_add_f32 v[14:15], v[14:15], v[20:21]
	v_lshlrev_b32_e32 v20, 16, v160
	v_and_b32_e32 v21, 0xffff0000, v160
	v_lshlrev_b32_e32 v22, 16, v161
	v_and_b32_e32 v23, 0xffff0000, v161
	v_pk_add_f32 v[12:13], v[12:13], v[22:23]
	s_and_b64 vcc, exec, s[42:43]
	v_pk_add_f32 v[10:11], v[10:11], v[20:21]
	s_cbranch_vccnz .LBB0_756
	v_cvt_pk_bf16_f32 v20, v14, v15
	v_cvt_pk_bf16_f32 v21, v16, v17
	v_cvt_pk_bf16_f32 v22, v10, v11
	v_cvt_pk_bf16_f32 v23, v12, v13
	global_store_dwordx4 v[94:95], v[20:23], off
.LBB0_756:
	s_nop 0
	v_lshlrev_b32_e32 v20, 16, v162
	v_and_b32_e32 v21, 0xffff0000, v162
	v_lshlrev_b32_e32 v22, 16, v163
	v_and_b32_e32 v23, 0xffff0000, v163
	v_pk_add_f32 v[8:9], v[8:9], v[22:23]
	v_pk_add_f32 v[6:7], v[6:7], v[20:21]
	v_lshlrev_b32_e32 v20, 16, v164
	v_and_b32_e32 v21, 0xffff0000, v164
	v_lshlrev_b32_e32 v22, 16, v165
	v_and_b32_e32 v23, 0xffff0000, v165
	v_pk_add_f32 v[4:5], v[4:5], v[22:23]
	s_and_b64 vcc, exec, s[42:43]
	v_pk_add_f32 v[2:3], v[2:3], v[20:21]
	s_cbranch_vccnz .LBB0_758
	v_cvt_pk_bf16_f32 v20, v6, v7
	v_cvt_pk_bf16_f32 v21, v8, v9
	v_cvt_pk_bf16_f32 v22, v2, v3
	v_cvt_pk_bf16_f32 v23, v4, v5
	global_store_dwordx4 v[94:95], v[20:23], off offset:256

.LBB0_971:
	v_lshl_add_u32 v168, s30, 8, v176
	v_lshl_or_b32 v170, s29, 8, v201
	v_ashrrev_i32_e32 v169, 31, v168
	v_ashrrev_i32_e32 v171, 31, v170
	v_lshlrev_b64 v[130:131], 11, v[168:169]
	v_or_b32_e32 v194, 16, v168
	v_lshl_add_u64 v[130:131], s[64:65], 0, v[130:131]
	v_lshlrev_b64 v[172:173], 1, v[170:171]
	v_ashrrev_i32_e32 v195, 31, v194
	v_lshl_add_u64 v[196:197], v[130:131], 0, v[172:173]
	v_lshlrev_b64 v[130:131], 11, v[194:195]
	v_or_b32_e32 v190, 32, v168
	v_lshl_add_u64 v[130:131], s[64:65], 0, v[130:131]
	v_ashrrev_i32_e32 v191, 31, v190
	v_lshl_add_u64 v[192:193], v[130:131], 0, v[172:173]
	v_lshlrev_b64 v[130:131], 11, v[190:191]
	v_or_b32_e32 v186, 48, v168
	v_lshl_add_u64 v[130:131], s[64:65], 0, v[130:131]
	v_ashrrev_i32_e32 v187, 31, v186
	v_lshl_add_u64 v[188:189], v[130:131], 0, v[172:173]
	v_lshlrev_b64 v[130:131], 11, v[186:187]
	v_lshl_add_u64 v[130:131], s[64:65], 0, v[130:131]
	v_lshl_add_u64 v[174:175], v[130:131], 0, v[172:173]
	s_mov_b32 s98, 0x40000
	s_mov_b32 s99, 0
	v_lshl_add_u64 v[166:167], v[196:197], 0, s[98:99]
	global_load_dwordx4 v[226:229], v[166:167], off
	global_load_dwordx4 v[212:215], v[196:197], off
	v_lshl_add_u64 v[166:167], v[196:197], 0, s[98:99]
	global_load_dwordx4 v[230:233], v[166:167], off offset:256
	global_load_dwordx4 v[154:157], v[196:197], off offset:256
	v_lshl_add_u64 v[166:167], v[192:193], 0, s[98:99]
	global_load_dwordx4 v[234:237], v[166:167], off
	global_load_dwordx4 v[150:153], v[192:193], off
	v_lshl_add_u64 v[166:167], v[192:193], 0, s[98:99]
	global_load_dwordx4 v[240:243], v[166:167], off offset:256
	global_load_dwordx4 v[146:149], v[192:193], off offset:256
	v_lshl_add_u64 v[166:167], v[188:189], 0, s[98:99]
	global_load_dwordx4 v[244:247], v[166:167], off
	global_load_dwordx4 v[142:145], v[188:189], off
	v_lshl_add_u64 v[166:167], v[188:189], 0, s[98:99]
	global_load_dwordx4 v[248:251], v[166:167], off offset:256
	global_load_dwordx4 v[138:141], v[188:189], off offset:256
	v_lshl_add_u64 v[166:167], v[174:175], 0, s[98:99]
	global_load_dwordx4 v[158:161], v[166:167], off
	global_load_dwordx4 v[134:137], v[174:175], off
	v_lshl_add_u64 v[166:167], v[174:175], 0, s[98:99]
	global_load_dwordx4 v[162:165], v[166:167], off offset:256
	global_load_dwordx4 v[130:133], v[174:175], off offset:256
	v_lshlrev_b64 v[198:199], 12, v[168:169]
	s_waitcnt vmcnt(0)
	v_lshlrev_b32_e32 v222, 16, v212
	v_and_b32_e32 v223, 0xffff0000, v212
	v_lshlrev_b32_e32 v212, 16, v213
	v_and_b32_e32 v213, 0xffff0000, v213
	v_pk_add_f32 v[128:129], v[128:129], v[212:213]
	v_lshlrev_b32_e32 v212, 16, v214
	v_and_b32_e32 v213, 0xffff0000, v214
	v_lshlrev_b32_e32 v214, 16, v215
	v_and_b32_e32 v215, 0xffff0000, v215
	v_cndmask_b32_e64 v203, 0, 1, s[82:83]
	v_lshl_add_u64 v[198:199], s[48:49], 0, v[198:199]
	v_pk_add_f32 v[126:127], v[126:127], v[222:223]
	v_pk_add_f32 v[124:125], v[124:125], v[214:215]
	v_pk_add_f32 v[122:123], v[122:123], v[212:213]
	v_cmp_ne_u32_e64 s[44:45], 1, v203
	s_andn2_b64 vcc, exec, s[82:83]
	v_lshl_add_u64 v[198:199], v[170:171], 2, v[198:199]
	s_cbranch_vccnz .LBB0_973
	global_store_dwordx4 v[198:199], v[126:129], off
	global_store_dwordx4 v[198:199], v[122:125], off offset:16

.LBB0_1003:
	v_mul_f32_e32 v79, v79, v79
	v_mul_f32_e32 v75, v75, v75
	v_mul_f32_e32 v71, v71, v71
	v_mul_f32_e32 v67, v67, v67
	v_fmac_f32_e32 v79, v78, v78
	v_mul_f32_e32 v78, v81, v81
	v_fmac_f32_e32 v75, v74, v74
	v_mul_f32_e32 v74, v77, v77
	v_fmac_f32_e32 v71, v70, v70
	v_mul_f32_e32 v70, v73, v73
	v_fmac_f32_e32 v67, v66, v66
	v_mul_f32_e32 v66, v69, v69
	v_fmac_f32_e32 v78, v80, v80
	v_fmac_f32_e32 v74, v76, v76
	v_fmac_f32_e32 v70, v72, v72
	v_fmac_f32_e32 v66, v68, v68
	v_add_f32_e32 v78, v79, v78
	v_add_f32_e32 v74, v75, v74
	v_add_f32_e32 v70, v71, v70
	v_add_f32_e32 v66, v67, v66
	v_add_f32_e32 v74, v78, v74
	v_add_f32_e32 v66, v70, v66
	v_add_f32_e32 v66, v74, v66
	ds_bpermute_b32 v67, v122, v66
	v_add_u32_e32 v108, 0x80, v168
	v_ashrrev_i32_e32 v109, 31, v108
	v_add_u32_e32 v104, 0x90, v168
	v_ashrrev_i32_e32 v105, 31, v104
	s_waitcnt lgkmcnt(0)
	v_add_f32_e32 v114, v66, v67
	v_lshlrev_b64 v[66:67], 11, v[108:109]
	v_lshl_add_u64 v[66:67], s[64:65], 0, v[66:67]
	v_lshl_add_u64 v[106:107], v[66:67], 0, v[172:173]
	v_lshlrev_b64 v[66:67], 11, v[104:105]
	v_add_u32_e32 v100, 0xa0, v168
	v_lshl_add_u64 v[66:67], s[64:65], 0, v[66:67]
	v_ashrrev_i32_e32 v101, 31, v100
	v_lshl_add_u64 v[102:103], v[66:67], 0, v[172:173]
	v_lshlrev_b64 v[66:67], 11, v[100:101]
	v_add_u32_e32 v96, 0xb0, v168
	v_lshl_add_u64 v[66:67], s[64:65], 0, v[66:67]
	v_ashrrev_i32_e32 v97, 31, v96
	v_lshl_add_u64 v[98:99], v[66:67], 0, v[172:173]
	v_lshlrev_b64 v[66:67], 11, v[96:97]
	v_lshl_add_u64 v[66:67], s[64:65], 0, v[66:67]
	v_lshl_add_u64 v[94:95], v[66:67], 0, v[172:173]
	ds_bpermute_b32 v115, v118, v114
	v_lshlrev_b64 v[108:109], 12, v[108:109]
	v_lshlrev_b32_e32 v120, 16, v226
	v_and_b32_e32 v121, 0xffff0000, v226
	v_lshlrev_b32_e32 v124, 16, v227
	v_and_b32_e32 v125, 0xffff0000, v227
	v_pk_add_f32 v[64:65], v[64:65], v[124:125]
	v_pk_add_f32 v[62:63], v[62:63], v[120:121]
	v_lshlrev_b32_e32 v120, 16, v228
	v_and_b32_e32 v121, 0xffff0000, v228
	v_lshlrev_b32_e32 v124, 16, v229
	v_and_b32_e32 v125, 0xffff0000, v229
	v_lshl_add_u64 v[108:109], s[48:49], 0, v[108:109]
	v_pk_add_f32 v[60:61], v[60:61], v[124:125]
	v_pk_add_f32 v[58:59], v[58:59], v[120:121]
	s_and_b64 vcc, exec, s[44:45]
	v_lshl_add_u64 v[108:109], v[170:171], 2, v[108:109]
	s_cbranch_vccnz .LBB0_1005
	global_store_dwordx4 v[108:109], v[62:65], off
	global_store_dwordx4 v[108:109], v[58:61], off offset:16

.LBB0_1007:
	v_lshlrev_b32_e32 v120, 16, v230
	v_and_b32_e32 v121, 0xffff0000, v230
	v_lshlrev_b32_e32 v90, 16, v231
	v_and_b32_e32 v91, 0xffff0000, v231
	v_pk_add_f32 v[56:57], v[56:57], v[90:91]
	v_lshlrev_b32_e32 v90, 16, v232
	v_and_b32_e32 v91, 0xffff0000, v232
	v_lshlrev_b32_e32 v92, 16, v233
	v_and_b32_e32 v93, 0xffff0000, v233
	v_pk_add_f32 v[54:55], v[54:55], v[120:121]
	v_pk_add_f32 v[52:53], v[52:53], v[92:93]
	s_and_b64 vcc, exec, s[44:45]
	v_pk_add_f32 v[50:51], v[50:51], v[90:91]
	s_cbranch_vccnz .LBB0_1009
	global_store_dwordx4 v[108:109], v[54:57], off offset:512
	global_store_dwordx4 v[108:109], v[50:53], off offset:528

.LBB0_1011:
	v_mul_f32_e32 v63, v63, v63
	v_mul_f32_e32 v59, v59, v59
	v_mul_f32_e32 v55, v55, v55
	v_mul_f32_e32 v51, v51, v51
	v_fmac_f32_e32 v63, v62, v62
	v_mul_f32_e32 v62, v65, v65
	v_fmac_f32_e32 v59, v58, v58
	v_mul_f32_e32 v58, v61, v61
	v_fmac_f32_e32 v55, v54, v54
	v_mul_f32_e32 v54, v57, v57
	v_fmac_f32_e32 v51, v50, v50
	v_mul_f32_e32 v50, v53, v53
	v_fmac_f32_e32 v62, v64, v64
	v_fmac_f32_e32 v58, v60, v60
	v_fmac_f32_e32 v54, v56, v56
	v_fmac_f32_e32 v50, v52, v52
	v_add_f32_e32 v62, v63, v62
	v_add_f32_e32 v58, v59, v58
	v_add_f32_e32 v54, v55, v54
	v_add_f32_e32 v50, v51, v50
	v_add_f32_e32 v58, v62, v58
	v_add_f32_e32 v50, v54, v50
	v_add_f32_e32 v50, v58, v50
	ds_bpermute_b32 v51, v122, v50
	v_lshlrev_b32_e32 v54, 16, v234
	v_and_b32_e32 v55, 0xffff0000, v234
	v_lshlrev_b32_e32 v56, 16, v235
	v_and_b32_e32 v57, 0xffff0000, v235
	s_waitcnt lgkmcnt(0)
	v_add_f32_e32 v52, v50, v51
	ds_bpermute_b32 v53, v118, v52
	v_lshlrev_b64 v[50:51], 12, v[104:105]
	v_pk_add_f32 v[48:49], v[48:49], v[56:57]
	v_pk_add_f32 v[46:47], v[46:47], v[54:55]
	v_lshlrev_b32_e32 v54, 16, v236
	v_and_b32_e32 v55, 0xffff0000, v236
	v_lshlrev_b32_e32 v56, 16, v237
	v_and_b32_e32 v57, 0xffff0000, v237
	v_lshl_add_u64 v[50:51], s[48:49], 0, v[50:51]
	v_pk_add_f32 v[44:45], v[44:45], v[56:57]
	v_pk_add_f32 v[42:43], v[42:43], v[54:55]
	s_and_b64 vcc, exec, s[44:45]
	v_lshl_add_u64 v[50:51], v[170:171], 2, v[50:51]
	s_cbranch_vccnz .LBB0_1013
	global_store_dwordx4 v[50:51], v[46:49], off
	global_store_dwordx4 v[50:51], v[42:45], off offset:16

.LBB0_1015:
	s_nop 0
	v_lshlrev_b32_e32 v54, 16, v240
	v_and_b32_e32 v55, 0xffff0000, v240
	v_lshlrev_b32_e32 v56, 16, v241
	v_and_b32_e32 v57, 0xffff0000, v241
	v_pk_add_f32 v[40:41], v[40:41], v[56:57]
	v_pk_add_f32 v[38:39], v[38:39], v[54:55]
	v_lshlrev_b32_e32 v54, 16, v242
	v_and_b32_e32 v55, 0xffff0000, v242
	v_lshlrev_b32_e32 v56, 16, v243
	v_and_b32_e32 v57, 0xffff0000, v243
	v_pk_add_f32 v[36:37], v[36:37], v[56:57]
	s_and_b64 vcc, exec, s[44:45]
	v_pk_add_f32 v[34:35], v[34:35], v[54:55]
	s_cbranch_vccnz .LBB0_1017
	global_store_dwordx4 v[50:51], v[38:41], off offset:512
	global_store_dwordx4 v[50:51], v[34:37], off offset:528

.LBB0_1019:
	v_mul_f32_e32 v47, v47, v47
	v_mul_f32_e32 v43, v43, v43
	v_mul_f32_e32 v39, v39, v39
	v_mul_f32_e32 v35, v35, v35
	v_fmac_f32_e32 v47, v46, v46
	v_mul_f32_e32 v46, v49, v49
	v_fmac_f32_e32 v43, v42, v42
	v_mul_f32_e32 v42, v45, v45
	v_fmac_f32_e32 v39, v38, v38
	v_mul_f32_e32 v38, v41, v41
	v_fmac_f32_e32 v35, v34, v34
	v_mul_f32_e32 v34, v37, v37
	v_fmac_f32_e32 v46, v48, v48
	v_fmac_f32_e32 v42, v44, v44
	v_fmac_f32_e32 v38, v40, v40
	v_fmac_f32_e32 v34, v36, v36
	v_add_f32_e32 v46, v47, v46
	v_add_f32_e32 v42, v43, v42
	v_add_f32_e32 v38, v39, v38
	v_add_f32_e32 v34, v35, v34
	v_add_f32_e32 v42, v46, v42
	v_add_f32_e32 v34, v38, v34
	v_add_f32_e32 v34, v42, v34
	ds_bpermute_b32 v35, v122, v34
	v_lshlrev_b32_e32 v38, 16, v244
	v_and_b32_e32 v39, 0xffff0000, v244
	v_lshlrev_b32_e32 v40, 16, v245
	v_and_b32_e32 v41, 0xffff0000, v245
	s_waitcnt lgkmcnt(0)
	v_add_f32_e32 v36, v34, v35
	ds_bpermute_b32 v37, v118, v36
	v_lshlrev_b64 v[34:35], 12, v[100:101]
	v_pk_add_f32 v[32:33], v[32:33], v[40:41]
	v_pk_add_f32 v[30:31], v[30:31], v[38:39]
	v_lshlrev_b32_e32 v38, 16, v246
	v_and_b32_e32 v39, 0xffff0000, v246
	v_lshlrev_b32_e32 v40, 16, v247
	v_and_b32_e32 v41, 0xffff0000, v247
	v_lshl_add_u64 v[34:35], s[48:49], 0, v[34:35]
	v_pk_add_f32 v[28:29], v[28:29], v[40:41]
	v_pk_add_f32 v[26:27], v[26:27], v[38:39]
	s_and_b64 vcc, exec, s[44:45]
	v_lshl_add_u64 v[34:35], v[170:171], 2, v[34:35]
	s_cbranch_vccnz .LBB0_1021
	global_store_dwordx4 v[34:35], v[30:33], off
	global_store_dwordx4 v[34:35], v[26:29], off offset:16

.LBB0_1023:
	s_nop 0
	v_lshlrev_b32_e32 v38, 16, v248
	v_and_b32_e32 v39, 0xffff0000, v248
	v_lshlrev_b32_e32 v40, 16, v249
	v_and_b32_e32 v41, 0xffff0000, v249
	v_pk_add_f32 v[24:25], v[24:25], v[40:41]
	v_pk_add_f32 v[22:23], v[22:23], v[38:39]
	v_lshlrev_b32_e32 v38, 16, v250
	v_and_b32_e32 v39, 0xffff0000, v250
	v_lshlrev_b32_e32 v40, 16, v251
	v_and_b32_e32 v41, 0xffff0000, v251
	v_pk_add_f32 v[20:21], v[20:21], v[40:41]
	s_and_b64 vcc, exec, s[44:45]
	v_pk_add_f32 v[18:19], v[18:19], v[38:39]
	s_cbranch_vccnz .LBB0_1025
	global_store_dwordx4 v[34:35], v[22:25], off offset:512
	global_store_dwordx4 v[34:35], v[18:21], off offset:528

.LBB0_1027:
	v_mul_f32_e32 v31, v31, v31
	v_mul_f32_e32 v27, v27, v27
	v_mul_f32_e32 v23, v23, v23
	v_mul_f32_e32 v19, v19, v19
	v_fmac_f32_e32 v31, v30, v30
	v_mul_f32_e32 v30, v33, v33
	v_fmac_f32_e32 v27, v26, v26
	v_mul_f32_e32 v26, v29, v29
	v_fmac_f32_e32 v23, v22, v22
	v_mul_f32_e32 v22, v25, v25
	v_fmac_f32_e32 v19, v18, v18
	v_mul_f32_e32 v18, v21, v21
	v_fmac_f32_e32 v30, v32, v32
	v_fmac_f32_e32 v26, v28, v28
	v_fmac_f32_e32 v22, v24, v24
	v_fmac_f32_e32 v18, v20, v20
	v_add_f32_e32 v30, v31, v30
	v_add_f32_e32 v26, v27, v26
	v_add_f32_e32 v22, v23, v22
	v_add_f32_e32 v18, v19, v18
	v_add_f32_e32 v26, v30, v26
	v_add_f32_e32 v18, v22, v18
	v_add_f32_e32 v18, v26, v18
	ds_bpermute_b32 v19, v122, v18
	v_lshlrev_b32_e32 v22, 16, v158
	v_and_b32_e32 v23, 0xffff0000, v158
	v_lshlrev_b32_e32 v24, 16, v159
	v_and_b32_e32 v25, 0xffff0000, v159
	s_waitcnt lgkmcnt(0)
	v_add_f32_e32 v20, v18, v19
	ds_bpermute_b32 v21, v118, v20
	v_lshlrev_b64 v[18:19], 12, v[96:97]
	v_pk_add_f32 v[16:17], v[16:17], v[24:25]
	v_pk_add_f32 v[14:15], v[14:15], v[22:23]
	v_lshlrev_b32_e32 v22, 16, v160
	v_and_b32_e32 v23, 0xffff0000, v160
	v_lshlrev_b32_e32 v24, 16, v161
	v_and_b32_e32 v25, 0xffff0000, v161
	v_lshl_add_u64 v[18:19], s[48:49], 0, v[18:19]
	v_pk_add_f32 v[12:13], v[12:13], v[24:25]
	v_pk_add_f32 v[10:11], v[10:11], v[22:23]
	s_and_b64 vcc, exec, s[44:45]
	v_lshl_add_u64 v[18:19], v[170:171], 2, v[18:19]
	s_cbranch_vccnz .LBB0_1029
	global_store_dwordx4 v[18:19], v[14:17], off
	global_store_dwordx4 v[18:19], v[10:13], off offset:16

.LBB0_1031:
	s_nop 0
	v_lshlrev_b32_e32 v22, 16, v162
	v_and_b32_e32 v23, 0xffff0000, v162
	v_lshlrev_b32_e32 v24, 16, v163
	v_and_b32_e32 v25, 0xffff0000, v163
	v_pk_add_f32 v[8:9], v[8:9], v[24:25]
	v_pk_add_f32 v[6:7], v[6:7], v[22:23]
	v_lshlrev_b32_e32 v22, 16, v164
	v_and_b32_e32 v23, 0xffff0000, v164
	v_lshlrev_b32_e32 v24, 16, v165
	v_and_b32_e32 v25, 0xffff0000, v165
	v_pk_add_f32 v[4:5], v[4:5], v[24:25]
	s_and_b64 vcc, exec, s[44:45]
	v_pk_add_f32 v[2:3], v[2:3], v[22:23]
	s_cbranch_vccnz .LBB0_1033
	global_store_dwordx4 v[18:19], v[6:9], off offset:512
	global_store_dwordx4 v[18:19], v[2:5], off offset:528

.LBB0_1061:
	s_lshl_b32 s0, s22, 8
	s_add_i32 s0, s0, s29
	v_or_b32_e32 v160, s0, v137
	s_lshl_b32 s0, s97, 8
	s_ashr_i32 s1, s0, 31
	s_lshl_b64 s[24:25], s[0:1], 1
	s_add_u32 s19, s64, s24
	s_addc_u32 s23, s65, s25
	s_lshl_b32 s24, s21, 1
	s_add_u32 s24, s19, s24
	s_addc_u32 s25, s23, 0
	v_mov_b32_e32 v137, v1
	v_ashrrev_i32_e32 v161, 31, v160
	v_lshl_add_u64 v[194:195], s[24:25], 0, v[136:137]
	v_lshlrev_b64 v[130:131], 11, v[160:161]
	v_or_b32_e32 v158, 16, v160
	v_lshl_add_u64 v[130:131], v[194:195], 0, v[130:131]
	v_ashrrev_i32_e32 v159, 31, v158
	s_barrier
	s_mov_b32 s98, 0x40000
	s_mov_b32 s99, 0
	v_lshl_add_u64 v[222:223], v[130:131], 0, s[98:99]
	global_load_dwordx4 v[212:215], v[222:223], off
	global_load_dwordx4 v[162:165], v[130:131], off
	v_lshl_add_u64 v[222:223], v[130:131], 0, s[98:99]
	global_load_dwordx4 v[226:229], v[222:223], off offset:256
	global_load_dwordx4 v[170:173], v[130:131], off offset:256
	v_lshlrev_b64 v[130:131], 11, v[158:159]
	v_or_b32_e32 v156, 32, v160
	v_lshl_add_u64 v[130:131], v[194:195], 0, v[130:131]
	v_ashrrev_i32_e32 v157, 31, v156
	v_lshl_add_u64 v[222:223], v[130:131], 0, s[98:99]
	global_load_dwordx4 v[230:233], v[222:223], off
	global_load_dwordx4 v[150:153], v[130:131], off
	v_lshl_add_u64 v[222:223], v[130:131], 0, s[98:99]
	global_load_dwordx4 v[234:237], v[222:223], off offset:256
	global_load_dwordx4 v[146:149], v[130:131], off offset:256
	v_lshlrev_b64 v[130:131], 11, v[156:157]
	v_or_b32_e32 v154, 48, v160
	v_lshl_add_u64 v[130:131], v[194:195], 0, v[130:131]
	v_ashrrev_i32_e32 v155, 31, v154
	v_lshl_add_u64 v[222:223], v[130:131], 0, s[98:99]
	global_load_dwordx4 v[240:243], v[222:223], off
	global_load_dwordx4 v[142:145], v[130:131], off
	v_lshl_add_u64 v[222:223], v[130:131], 0, s[98:99]
	global_load_dwordx4 v[244:247], v[222:223], off offset:256
	global_load_dwordx4 v[138:141], v[130:131], off offset:256
	v_lshlrev_b64 v[130:131], 11, v[154:155]
	v_lshl_add_u64 v[130:131], v[194:195], 0, v[130:131]
	v_lshl_add_u64 v[222:223], v[130:131], 0, s[98:99]
	global_load_dwordx4 v[248:251], v[222:223], off
	global_load_dwordx4 v[134:137], v[130:131], off
	s_nop 0
	global_load_dwordx4 v[130:133], v[130:131], off offset:256
	v_cmp_lt_i32_e32 vcc, v210, v206
	s_nop 1
	v_cndmask_b32_e32 v0, v205, v210, vcc
	v_cmp_lt_i32_e32 vcc, v209, v206
	v_lshlrev_b32_e32 v0, 2, v0
	s_nop 0
	v_cndmask_b32_e32 v166, v205, v209, vcc
	v_lshlrev_b32_e32 v198, 2, v166
	v_cmp_eq_u32_e32 vcc, 0, v176
	s_waitcnt vmcnt(0)
	v_lshlrev_b32_e32 v166, 16, v162
	v_and_b32_e32 v167, 0xffff0000, v162
	v_lshlrev_b32_e32 v162, 16, v163
	v_and_b32_e32 v163, 0xffff0000, v163
	v_pk_add_f32 v[162:163], v[128:129], v[162:163]
	v_pk_add_f32 v[166:167], v[126:127], v[166:167]
	v_mul_f32_e32 v127, v163, v163
	v_mul_f32_e32 v126, v167, v167
	v_fmac_f32_e32 v126, v166, v166
	v_fmac_f32_e32 v127, v162, v162
	v_add_f32_e32 v168, v126, v127
	v_lshlrev_b32_e32 v126, 16, v164
	v_and_b32_e32 v127, 0xffff0000, v164
	v_lshlrev_b32_e32 v128, 16, v165
	v_and_b32_e32 v129, 0xffff0000, v165
	v_pk_add_f32 v[128:129], v[124:125], v[128:129]
	v_pk_add_f32 v[164:165], v[122:123], v[126:127]
	v_mul_f32_e32 v123, v129, v129
	v_mul_f32_e32 v122, v165, v165
	v_fmac_f32_e32 v122, v164, v164
	v_fmac_f32_e32 v123, v128, v128
	v_add_f32_e32 v122, v122, v123
	v_add_f32_e32 v126, v168, v122
	v_lshlrev_b32_e32 v122, 16, v170
	v_and_b32_e32 v123, 0xffff0000, v170
	v_lshlrev_b32_e32 v124, 16, v171
	v_and_b32_e32 v125, 0xffff0000, v171
	v_pk_add_f32 v[168:169], v[120:121], v[124:125]
	v_pk_add_f32 v[170:171], v[118:119], v[122:123]
	v_mul_f32_e32 v119, v169, v169
	v_mul_f32_e32 v118, v171, v171
	v_fmac_f32_e32 v118, v170, v170
	v_fmac_f32_e32 v119, v168, v168
	v_add_f32_e32 v118, v118, v119
	v_add_f32_e32 v122, v126, v118
	v_lshlrev_b32_e32 v118, 16, v172
	v_and_b32_e32 v119, 0xffff0000, v172
	v_lshlrev_b32_e32 v120, 16, v173
	v_and_b32_e32 v121, 0xffff0000, v173
	v_pk_add_f32 v[172:173], v[116:117], v[120:121]
	v_pk_add_f32 v[174:175], v[114:115], v[118:119]
	v_mul_f32_e32 v115, v173, v173
	v_mul_f32_e32 v114, v175, v175
	v_fmac_f32_e32 v114, v174, v174
	v_fmac_f32_e32 v115, v172, v172
	v_add_f32_e32 v114, v114, v115
	v_add_f32_e32 v114, v122, v114
	ds_bpermute_b32 v115, v0, v114
	v_readlane_b32 s12, v253, 14
	v_readlane_b32 s13, v253, 15
	s_waitcnt lgkmcnt(0)
	v_add_f32_e32 v114, v114, v115
	ds_bpermute_b32 v115, v198, v114
	v_lshl_add_u64 v[186:187], v[160:161], 3, s[12:13]
	s_and_saveexec_b64 s[38:39], vcc
	v_readlane_b32 s51, v255, 58
	s_mov_b32 s50, 0x8000
	s_cbranch_execz .LBB0_1063
	s_waitcnt lgkmcnt(0)
	v_add_f32_e32 v114, v114, v115
	v_fma_f32 v114, v114, s17, 0.5
	v_trunc_f32_e32 v114, v114
	v_mul_f32_e32 v115, 0x2f800000, v114
	v_floor_f32_e32 v115, v115
	v_fmac_f32_e32 v114, 0xcf800000, v115
	v_cvt_u32_f32_e32 v114, v114
	v_cvt_u32_f32_e32 v115, v115
	global_atomic_add_x2 v[186:187], v[114:115], off

.LBB0_1069:
	s_or_b64 exec, exec, s[38:39]
	v_add_u32_e32 v96, 0x80, v160
	v_ashrrev_i32_e32 v97, 31, v96
	s_waitcnt lgkmcnt(0)
	v_lshlrev_b64 v[66:67], 11, v[96:97]
	v_add_u32_e32 v94, 0x90, v160
	v_lshl_add_u64 v[66:67], v[194:195], 0, v[66:67]
	v_ashrrev_i32_e32 v95, 31, v94
	v_lshlrev_b64 v[66:67], 11, v[94:95]
	v_add_u32_e32 v92, 0xa0, v160
	v_lshl_add_u64 v[66:67], v[194:195], 0, v[66:67]
	v_ashrrev_i32_e32 v93, 31, v92
	v_lshlrev_b64 v[66:67], 11, v[92:93]
	v_add_u32_e32 v90, 0xb0, v160
	v_lshl_add_u64 v[66:67], v[194:195], 0, v[66:67]
	v_ashrrev_i32_e32 v91, 31, v90
	v_lshlrev_b64 v[66:67], 11, v[90:91]
	v_lshl_add_u64 v[66:67], v[194:195], 0, v[66:67]
	s_nop 0
	global_load_dwordx4 v[66:69], v[66:67], off offset:256
	v_lshlrev_b32_e32 v144, 16, v212
	v_and_b32_e32 v145, 0xffff0000, v212
	v_lshlrev_b32_e32 v134, 16, v213
	v_and_b32_e32 v135, 0xffff0000, v213
	v_pk_add_f32 v[64:65], v[64:65], v[134:135]
	v_pk_add_f32 v[62:63], v[62:63], v[144:145]
	v_mul_f32_e32 v135, v65, v65
	v_mul_f32_e32 v134, v63, v63
	v_fmac_f32_e32 v134, v62, v62
	v_fmac_f32_e32 v135, v64, v64
	v_add_f32_e32 v144, v134, v135
	v_lshlrev_b32_e32 v134, 16, v214
	v_and_b32_e32 v135, 0xffff0000, v214
	v_lshlrev_b32_e32 v136, 16, v215
	v_and_b32_e32 v137, 0xffff0000, v215
	v_pk_add_f32 v[60:61], v[60:61], v[136:137]
	v_pk_add_f32 v[58:59], v[58:59], v[134:135]
	v_mul_f32_e32 v135, v61, v61
	v_mul_f32_e32 v134, v59, v59
	v_fmac_f32_e32 v134, v58, v58
	v_fmac_f32_e32 v135, v60, v60
	v_add_f32_e32 v134, v134, v135
	v_add_f32_e32 v144, v144, v134
	v_lshlrev_b32_e32 v134, 16, v226
	v_and_b32_e32 v135, 0xffff0000, v226
	v_lshlrev_b32_e32 v136, 16, v227
	v_and_b32_e32 v137, 0xffff0000, v227
	v_pk_add_f32 v[56:57], v[56:57], v[136:137]
	v_pk_add_f32 v[134:135], v[54:55], v[134:135]
	v_mul_f32_e32 v55, v57, v57
	v_mul_f32_e32 v54, v135, v135
	v_fmac_f32_e32 v54, v134, v134
	v_fmac_f32_e32 v55, v56, v56
	v_add_f32_e32 v54, v54, v55
	v_add_f32_e32 v194, v144, v54
	v_lshlrev_b32_e32 v54, 16, v228
	v_and_b32_e32 v55, 0xffff0000, v228
	v_lshlrev_b32_e32 v136, 16, v229
	v_and_b32_e32 v137, 0xffff0000, v229
	v_pk_add_f32 v[136:137], v[52:53], v[136:137]
	v_pk_add_f32 v[144:145], v[50:51], v[54:55]
	v_mul_f32_e32 v51, v137, v137
	v_mul_f32_e32 v50, v145, v145
	v_fmac_f32_e32 v50, v144, v144
	v_fmac_f32_e32 v51, v136, v136
	v_add_f32_e32 v50, v50, v51
	v_add_f32_e32 v50, v194, v50
	ds_bpermute_b32 v51, v0, v50
	v_readlane_b32 s12, v253, 14
	v_readlane_b32 s13, v253, 15
	s_waitcnt lgkmcnt(0)
	v_add_f32_e32 v50, v50, v51
	ds_bpermute_b32 v51, v198, v50
	v_lshl_add_u64 v[194:195], v[96:97], 3, s[12:13]
	s_and_saveexec_b64 s[38:39], vcc
	s_cbranch_execz .LBB0_1071
	s_waitcnt lgkmcnt(0)
	v_add_f32_e32 v50, v50, v51
	v_fma_f32 v50, v50, s17, 0.5
	v_trunc_f32_e32 v50, v50
	v_mul_f32_e32 v51, 0x2f800000, v50
	v_floor_f32_e32 v51, v51
	v_fmac_f32_e32 v50, 0xcf800000, v51
	v_cvt_u32_f32_e32 v50, v50
	v_cvt_u32_f32_e32 v51, v51
	global_atomic_add_x2 v[194:195], v[50:51], off
.LBB0_1071:
	s_or_b64 exec, exec, s[38:39]
	v_lshlrev_b32_e32 v50, 16, v230
	s_waitcnt lgkmcnt(0)
	v_and_b32_e32 v51, 0xffff0000, v230
	v_lshlrev_b32_e32 v52, 16, v231
	v_and_b32_e32 v53, 0xffff0000, v231
	v_pk_add_f32 v[48:49], v[48:49], v[52:53]
	v_pk_add_f32 v[46:47], v[46:47], v[50:51]
	v_mul_f32_e32 v51, v49, v49
	v_mul_f32_e32 v50, v47, v47
	v_fmac_f32_e32 v50, v46, v46
	v_fmac_f32_e32 v51, v48, v48
	v_add_f32_e32 v54, v50, v51
	v_lshlrev_b32_e32 v50, 16, v232
	v_and_b32_e32 v51, 0xffff0000, v232
	v_lshlrev_b32_e32 v52, 16, v233
	v_and_b32_e32 v53, 0xffff0000, v233
	v_pk_add_f32 v[44:45], v[44:45], v[52:53]
	v_pk_add_f32 v[42:43], v[42:43], v[50:51]
	v_mul_f32_e32 v51, v45, v45
	v_mul_f32_e32 v50, v43, v43
	v_fmac_f32_e32 v50, v42, v42
	v_fmac_f32_e32 v51, v44, v44
	v_add_f32_e32 v50, v50, v51
	v_add_f32_e32 v86, v54, v50
	v_lshlrev_b32_e32 v50, 16, v234
	v_and_b32_e32 v51, 0xffff0000, v234
	v_lshlrev_b32_e32 v52, 16, v235
	v_and_b32_e32 v53, 0xffff0000, v235
	v_pk_add_f32 v[40:41], v[40:41], v[52:53]
	v_pk_add_f32 v[54:55], v[38:39], v[50:51]
	v_mul_f32_e32 v39, v41, v41
	v_mul_f32_e32 v38, v55, v55
	v_fmac_f32_e32 v38, v54, v54
	v_fmac_f32_e32 v39, v40, v40
	v_add_f32_e32 v38, v38, v39
	v_add_f32_e32 v52, v86, v38
	v_lshlrev_b32_e32 v38, 16, v236
	v_and_b32_e32 v39, 0xffff0000, v236
	v_lshlrev_b32_e32 v50, 16, v237
	v_and_b32_e32 v51, 0xffff0000, v237
	v_pk_add_f32 v[82:83], v[36:37], v[50:51]
	v_pk_add_f32 v[84:85], v[34:35], v[38:39]
	v_mul_f32_e32 v35, v83, v83
	v_mul_f32_e32 v34, v85, v85
	v_fmac_f32_e32 v34, v84, v84
	v_fmac_f32_e32 v35, v82, v82
	v_add_f32_e32 v34, v34, v35
	v_add_f32_e32 v34, v52, v34
	ds_bpermute_b32 v35, v0, v34
	v_readlane_b32 s12, v253, 14
	v_readlane_b32 s13, v253, 15
	s_waitcnt lgkmcnt(0)
	v_add_f32_e32 v34, v34, v35
	ds_bpermute_b32 v35, v198, v34
	v_lshl_add_u64 v[88:89], v[94:95], 3, s[12:13]
	s_and_saveexec_b64 s[38:39], vcc
	s_cbranch_execz .LBB0_1073
	s_waitcnt lgkmcnt(0)
	v_add_f32_e32 v34, v34, v35
	v_fma_f32 v34, v34, s17, 0.5
	v_trunc_f32_e32 v34, v34
	v_mul_f32_e32 v35, 0x2f800000, v34
	v_floor_f32_e32 v35, v35
	v_fmac_f32_e32 v34, 0xcf800000, v35
	v_cvt_u32_f32_e32 v34, v34
	v_cvt_u32_f32_e32 v35, v35
	global_atomic_add_x2 v[88:89], v[34:35], off
.LBB0_1073:
	s_or_b64 exec, exec, s[38:39]
	v_lshlrev_b32_e32 v34, 16, v240
	s_waitcnt lgkmcnt(0)
	v_and_b32_e32 v35, 0xffff0000, v240
	v_lshlrev_b32_e32 v36, 16, v241
	v_and_b32_e32 v37, 0xffff0000, v241
	v_pk_add_f32 v[32:33], v[32:33], v[36:37]
	v_pk_add_f32 v[30:31], v[30:31], v[34:35]
	v_mul_f32_e32 v35, v33, v33
	v_mul_f32_e32 v34, v31, v31
	v_fmac_f32_e32 v34, v30, v30
	v_fmac_f32_e32 v35, v32, v32
	v_add_f32_e32 v38, v34, v35
	v_lshlrev_b32_e32 v34, 16, v242
	v_and_b32_e32 v35, 0xffff0000, v242
	v_lshlrev_b32_e32 v36, 16, v243
	v_and_b32_e32 v37, 0xffff0000, v243
	v_pk_add_f32 v[28:29], v[28:29], v[36:37]
	v_pk_add_f32 v[34:35], v[26:27], v[34:35]
	v_mul_f32_e32 v27, v29, v29
	v_mul_f32_e32 v26, v35, v35
	v_fmac_f32_e32 v26, v34, v34
	v_fmac_f32_e32 v27, v28, v28
	v_add_f32_e32 v26, v26, v27
	v_add_f32_e32 v38, v38, v26
	v_lshlrev_b32_e32 v26, 16, v244
	v_and_b32_e32 v27, 0xffff0000, v244
	v_lshlrev_b32_e32 v36, 16, v245
	v_and_b32_e32 v37, 0xffff0000, v245
	v_pk_add_f32 v[36:37], v[24:25], v[36:37]
	v_pk_add_f32 v[52:53], v[22:23], v[26:27]
	v_mul_f32_e32 v23, v37, v37
	v_mul_f32_e32 v22, v53, v53
	v_fmac_f32_e32 v22, v52, v52
	v_fmac_f32_e32 v23, v36, v36
	v_add_f32_e32 v22, v22, v23
	v_add_f32_e32 v26, v38, v22
	v_lshlrev_b32_e32 v22, 16, v246
	v_and_b32_e32 v23, 0xffff0000, v246
	v_lshlrev_b32_e32 v24, 16, v247
	v_and_b32_e32 v25, 0xffff0000, v247
	v_pk_add_f32 v[74:75], v[20:21], v[24:25]
	v_pk_add_f32 v[76:77], v[18:19], v[22:23]
	v_mul_f32_e32 v19, v75, v75
	v_mul_f32_e32 v18, v77, v77
	v_fmac_f32_e32 v18, v76, v76
	v_fmac_f32_e32 v19, v74, v74
	v_add_f32_e32 v18, v18, v19
	v_add_f32_e32 v18, v26, v18
	ds_bpermute_b32 v19, v0, v18
	v_readlane_b32 s12, v253, 14
	v_readlane_b32 s13, v253, 15
	s_waitcnt lgkmcnt(0)
	v_add_f32_e32 v18, v18, v19
	ds_bpermute_b32 v19, v198, v18
	v_lshl_add_u64 v[196:197], v[92:93], 3, s[12:13]
	s_and_saveexec_b64 s[38:39], vcc
	s_cbranch_execz .LBB0_1075
	s_waitcnt lgkmcnt(0)
	v_add_f32_e32 v18, v18, v19
	v_fma_f32 v18, v18, s17, 0.5
	v_trunc_f32_e32 v18, v18
	v_mul_f32_e32 v19, 0x2f800000, v18
	v_floor_f32_e32 v19, v19
	v_fmac_f32_e32 v18, 0xcf800000, v19
	v_cvt_u32_f32_e32 v18, v18
	v_cvt_u32_f32_e32 v19, v19
	global_atomic_add_x2 v[196:197], v[18:19], off
.LBB0_1075:
	s_or_b64 exec, exec, s[38:39]
	v_lshlrev_b32_e32 v20, 16, v248
	v_and_b32_e32 v21, 0xffff0000, v248
	v_lshlrev_b32_e32 v18, 16, v249
	s_waitcnt lgkmcnt(0)
	v_and_b32_e32 v19, 0xffff0000, v249
	v_pk_add_f32 v[18:19], v[16:17], v[18:19]
	v_pk_add_f32 v[22:23], v[14:15], v[20:21]
	v_mul_f32_e32 v15, v19, v19
	v_mul_f32_e32 v14, v23, v23
	v_fmac_f32_e32 v14, v22, v22
	v_fmac_f32_e32 v15, v18, v18
	v_add_f32_e32 v26, v14, v15
	v_lshlrev_b32_e32 v14, 16, v250
	v_and_b32_e32 v15, 0xffff0000, v250
	v_lshlrev_b32_e32 v16, 16, v251
	v_and_b32_e32 v17, 0xffff0000, v251
	v_pk_add_f32 v[20:21], v[12:13], v[16:17]
	v_pk_add_f32 v[24:25], v[10:11], v[14:15]
	v_mul_f32_e32 v11, v21, v21
	v_mul_f32_e32 v10, v25, v25
	v_fmac_f32_e32 v10, v24, v24
	v_fmac_f32_e32 v11, v20, v20
	v_add_f32_e32 v10, v10, v11
	v_add_f32_e32 v14, v26, v10
	s_waitcnt vmcnt(0)
	v_lshlrev_b32_e32 v10, 16, v66
	v_and_b32_e32 v11, 0xffff0000, v66
	v_lshlrev_b32_e32 v12, 16, v67
	v_and_b32_e32 v13, 0xffff0000, v67
	v_pk_add_f32 v[26:27], v[8:9], v[12:13]
	v_pk_add_f32 v[38:39], v[6:7], v[10:11]
	v_mul_f32_e32 v7, v27, v27
	v_mul_f32_e32 v6, v39, v39
	v_fmac_f32_e32 v6, v38, v38
	v_fmac_f32_e32 v7, v26, v26
	v_add_f32_e32 v6, v6, v7
	v_add_f32_e32 v10, v14, v6
	v_lshlrev_b32_e32 v6, 16, v68
	v_and_b32_e32 v7, 0xffff0000, v68
	v_lshlrev_b32_e32 v8, 16, v69
	v_and_b32_e32 v9, 0xffff0000, v69
	v_pk_add_f32 v[50:51], v[4:5], v[8:9]
	v_pk_add_f32 v[66:67], v[2:3], v[6:7]
	v_mul_f32_e32 v3, v51, v51
	v_mul_f32_e32 v2, v67, v67
	v_fmac_f32_e32 v2, v66, v66
	v_fmac_f32_e32 v3, v50, v50
	v_add_f32_e32 v2, v2, v3
	v_add_f32_e32 v2, v10, v2
	ds_bpermute_b32 v0, v0, v2
	v_readlane_b32 s12, v253, 14
	v_readlane_b32 s13, v253, 15
	s_waitcnt lgkmcnt(0)
	v_add_f32_e32 v0, v2, v0
	ds_bpermute_b32 v4, v198, v0
	v_lshl_add_u64 v[2:3], v[90:91], 3, s[12:13]
	s_and_saveexec_b64 s[38:39], vcc
	s_cbranch_execz .LBB0_1077
	s_waitcnt lgkmcnt(0)
	v_add_f32_e32 v0, v0, v4
	v_fma_f32 v0, v0, s17, 0.5
	v_trunc_f32_e32 v0, v0
	v_mul_f32_e32 v4, 0x2f800000, v0
	v_floor_f32_e32 v5, v4
	v_fmac_f32_e32 v0, 0xcf800000, v5
	v_cvt_u32_f32_e32 v4, v0
	v_cvt_u32_f32_e32 v5, v5
	global_atomic_add_x2 v[2:3], v[4:5], off
